# as v30 plus gate/up SwiGLU epilogue row groups re-emitted with packed f32 mul/add (45 instead of ~85 instructions per row group, identical arithmetic)
# baseline (speedup 1.0000x reference)
; __device__ __forceinline__ unsigned cvt_pk_bf16(float lo, float hi) { unsigned r; asm volatile("v_cvt_pk_bf16_f32 %0, %1, %2" : "=v"(r) : "v"(lo), "v"(hi)); return r; }
;     __device__ __forceinline__ void operator()(const f32x4 (&acc)[2][2][4][2], const Unit& u, int wr, int wc, int fr, int fq, const float (&rs)[2][4]) const {
;     ...
;         const int row0 = u.pm * BM + wr * 64 + fr, col0 = u.pn * HALF + wc * 32 + 8 * fq;
; #pragma unroll
;         for (int ai = 0; ai < 2; ++ai)
; #pragma unroll
;             for (int m = 0; m < 4; ++m) { bf16_t* rowp = O + (size_t)(row0 + ai * HALF + m * 16) * FF + col0;
;                 float r[8], e[8]; const float rsv = rs[ai][m]; const float c1 = -rsv * LOG2E, c2 = rsv * rsv;
; #pragma unroll
;                 for (int j = 0; j < 8; ++j) { const float gv = acc[ai][0][m][j >> 2][j & 3], uv = acc[ai][1][m][j >> 2][j & 3]; e[j] = gv * c1; r[j] = gv * uv; }
;                 __builtin_amdgcn_sched_barrier(0);
; #pragma unroll
;                 for (int j = 0; j < 8; ++j) e[j] = __builtin_amdgcn_exp2f(e[j]);
;                 __builtin_amdgcn_sched_barrier(0);
; #pragma unroll
;                 for (int j = 0; j < 8; ++j) e[j] = 1.0f + e[j];
;                 __builtin_amdgcn_sched_barrier(0);
; #pragma unroll
;                 for (int j = 0; j < 8; ++j) e[j] = __builtin_amdgcn_rcpf(e[j]);
;                 __builtin_amdgcn_sched_barrier(0);
; #pragma unroll
;                 for (int j = 0; j < 8; ++j) r[j] = r[j] * (c2 * e[j]);
;                 u32x4 w; w.x = cvt_pk_bf16(r[0], r[1]); w.y = cvt_pk_bf16(r[2], r[3]); w.z = cvt_pk_bf16(r[4], r[5]); w.w = cvt_pk_bf16(r[6], r[7]);
;                 *(u32x4*)rowp = w; }
.LBB0_609:
	s_lshl_b32 s0, s44, 8
	v_mov_b32_e32 v130, v168
	v_mov_b32_e32 v131, v166
	s_add_i32 s0, s0, s74
	s_nop 0
	v_add_u32_e32 v181, s0, v131
	s_lshl_b32 s0, s45, 7
	s_or_b32 s0, s0, s28
	v_lshl_add_u32 v164, v130, 3, s0
	v_ashrrev_i32_e32 v165, 31, v164
	v_lshl_add_u64 v[164:165], v[164:165], 1, s[36:37]
	v_mul_f32_e32 v250, 0xbfb8aa3b, v163
	v_mul_f32_e32 v251, v163, v163
	v_pk_mul_f32 v[242:243], v[126:127], v[250:251] op_sel_hi:[1,0]
	v_pk_mul_f32 v[244:245], v[128:129], v[250:251] op_sel_hi:[1,0]
	v_pk_mul_f32 v[246:247], v[118:119], v[250:251] op_sel_hi:[1,0]
	v_pk_mul_f32 v[248:249], v[120:121], v[250:251] op_sel_hi:[1,0]
	v_exp_f32_e32 v242, v242
	v_exp_f32_e32 v243, v243
	v_exp_f32_e32 v244, v244
	v_exp_f32_e32 v245, v245
	v_exp_f32_e32 v246, v246
	v_exp_f32_e32 v247, v247
	v_exp_f32_e32 v248, v248
	v_exp_f32_e32 v249, v249
	v_pk_add_f32 v[242:243], v[242:243], 1.0 op_sel_hi:[1,0]
	v_pk_add_f32 v[244:245], v[244:245], 1.0 op_sel_hi:[1,0]
	v_pk_add_f32 v[246:247], v[246:247], 1.0 op_sel_hi:[1,0]
	v_pk_add_f32 v[248:249], v[248:249], 1.0 op_sel_hi:[1,0]
	v_rcp_f32_e32 v242, v242
	v_rcp_f32_e32 v243, v243
	v_rcp_f32_e32 v244, v244
	v_rcp_f32_e32 v245, v245
	v_rcp_f32_e32 v246, v246
	v_rcp_f32_e32 v247, v247
	v_rcp_f32_e32 v248, v248
	v_rcp_f32_e32 v249, v249
	v_pk_mul_f32 v[126:127], v[126:127], v[122:123]
	v_pk_mul_f32 v[128:129], v[128:129], v[124:125]
	v_pk_mul_f32 v[118:119], v[118:119], v[114:115]
	v_pk_mul_f32 v[120:121], v[120:121], v[116:117]
	v_pk_mul_f32 v[242:243], v[242:243], v[250:251] op_sel:[0,1] op_sel_hi:[1,1]
	v_pk_mul_f32 v[244:245], v[244:245], v[250:251] op_sel:[0,1] op_sel_hi:[1,1]
	v_pk_mul_f32 v[246:247], v[246:247], v[250:251] op_sel:[0,1] op_sel_hi:[1,1]
	v_pk_mul_f32 v[248:249], v[248:249], v[250:251] op_sel:[0,1] op_sel_hi:[1,1]
	v_pk_mul_f32 v[126:127], v[126:127], v[242:243]
	v_pk_mul_f32 v[128:129], v[128:129], v[244:245]
	v_pk_mul_f32 v[118:119], v[118:119], v[246:247]
	v_pk_mul_f32 v[120:121], v[120:121], v[248:249]
	v_cvt_pk_bf16_f32 v122, v126, v127
	v_cvt_pk_bf16_f32 v123, v128, v129
	v_cvt_pk_bf16_f32 v124, v118, v119
	v_cvt_pk_bf16_f32 v125, v120, v121
	v_mad_i64_i32 v[238:239], s[0:1], v181, s11, v[164:165]
	global_store_dwordx4 v[238:239], v[122:125], off
	v_mul_f32_e32 v250, 0xbfb8aa3b, v162
	v_mul_f32_e32 v251, v162, v162
	v_pk_mul_f32 v[242:243], v[110:111], v[250:251] op_sel_hi:[1,0]
	v_pk_mul_f32 v[244:245], v[112:113], v[250:251] op_sel_hi:[1,0]
	v_pk_mul_f32 v[246:247], v[106:107], v[250:251] op_sel_hi:[1,0]
	v_pk_mul_f32 v[248:249], v[108:109], v[250:251] op_sel_hi:[1,0]
	v_exp_f32_e32 v242, v242
	v_exp_f32_e32 v243, v243
	v_exp_f32_e32 v244, v244
	v_exp_f32_e32 v245, v245
	v_exp_f32_e32 v246, v246
	v_exp_f32_e32 v247, v247
	v_exp_f32_e32 v248, v248
	v_exp_f32_e32 v249, v249
	v_pk_add_f32 v[242:243], v[242:243], 1.0 op_sel_hi:[1,0]
	v_pk_add_f32 v[244:245], v[244:245], 1.0 op_sel_hi:[1,0]
	v_pk_add_f32 v[246:247], v[246:247], 1.0 op_sel_hi:[1,0]
	v_pk_add_f32 v[248:249], v[248:249], 1.0 op_sel_hi:[1,0]
	v_rcp_f32_e32 v242, v242
	v_rcp_f32_e32 v243, v243
	v_rcp_f32_e32 v244, v244
	v_rcp_f32_e32 v245, v245
	v_rcp_f32_e32 v246, v246
	v_rcp_f32_e32 v247, v247
	v_rcp_f32_e32 v248, v248
	v_rcp_f32_e32 v249, v249
	v_pk_mul_f32 v[110:111], v[110:111], v[102:103]
	v_pk_mul_f32 v[112:113], v[112:113], v[104:105]
	v_pk_mul_f32 v[106:107], v[106:107], v[98:99]
	v_pk_mul_f32 v[108:109], v[108:109], v[100:101]
	v_pk_mul_f32 v[242:243], v[242:243], v[250:251] op_sel:[0,1] op_sel_hi:[1,1]
	v_pk_mul_f32 v[244:245], v[244:245], v[250:251] op_sel:[0,1] op_sel_hi:[1,1]
	v_pk_mul_f32 v[246:247], v[246:247], v[250:251] op_sel:[0,1] op_sel_hi:[1,1]
	v_pk_mul_f32 v[248:249], v[248:249], v[250:251] op_sel:[0,1] op_sel_hi:[1,1]
	v_pk_mul_f32 v[110:111], v[110:111], v[242:243]
	v_pk_mul_f32 v[112:113], v[112:113], v[244:245]
	v_pk_mul_f32 v[106:107], v[106:107], v[246:247]
	v_pk_mul_f32 v[108:109], v[108:109], v[248:249]
	v_cvt_pk_bf16_f32 v102, v110, v111
	v_cvt_pk_bf16_f32 v103, v112, v113
	v_cvt_pk_bf16_f32 v104, v106, v107
	v_cvt_pk_bf16_f32 v105, v108, v109
	v_add_u32_e32 v240, 16, v181
	v_mad_i64_i32 v[238:239], s[0:1], v240, s11, v[164:165]
	global_store_dwordx4 v[238:239], v[102:105], off
	v_mul_f32_e32 v250, 0xbfb8aa3b, v161
	v_mul_f32_e32 v251, v161, v161
	v_pk_mul_f32 v[242:243], v[94:95], v[250:251] op_sel_hi:[1,0]
	v_pk_mul_f32 v[244:245], v[96:97], v[250:251] op_sel_hi:[1,0]
	v_pk_mul_f32 v[246:247], v[86:87], v[250:251] op_sel_hi:[1,0]
	v_pk_mul_f32 v[248:249], v[88:89], v[250:251] op_sel_hi:[1,0]
	v_exp_f32_e32 v242, v242
	v_exp_f32_e32 v243, v243
	v_exp_f32_e32 v244, v244
	v_exp_f32_e32 v245, v245
	v_exp_f32_e32 v246, v246
	v_exp_f32_e32 v247, v247
	v_exp_f32_e32 v248, v248
	v_exp_f32_e32 v249, v249
	v_pk_add_f32 v[242:243], v[242:243], 1.0 op_sel_hi:[1,0]
	v_pk_add_f32 v[244:245], v[244:245], 1.0 op_sel_hi:[1,0]
	v_pk_add_f32 v[246:247], v[246:247], 1.0 op_sel_hi:[1,0]
	v_pk_add_f32 v[248:249], v[248:249], 1.0 op_sel_hi:[1,0]
	v_rcp_f32_e32 v242, v242
	v_rcp_f32_e32 v243, v243
	v_rcp_f32_e32 v244, v244
	v_rcp_f32_e32 v245, v245
	v_rcp_f32_e32 v246, v246
	v_rcp_f32_e32 v247, v247
	v_rcp_f32_e32 v248, v248
	v_rcp_f32_e32 v249, v249
	v_pk_mul_f32 v[94:95], v[94:95], v[90:91]
	v_pk_mul_f32 v[96:97], v[96:97], v[92:93]
	v_pk_mul_f32 v[86:87], v[86:87], v[82:83]
	v_pk_mul_f32 v[88:89], v[88:89], v[84:85]
	v_pk_mul_f32 v[242:243], v[242:243], v[250:251] op_sel:[0,1] op_sel_hi:[1,1]
	v_pk_mul_f32 v[244:245], v[244:245], v[250:251] op_sel:[0,1] op_sel_hi:[1,1]
	v_pk_mul_f32 v[246:247], v[246:247], v[250:251] op_sel:[0,1] op_sel_hi:[1,1]
	v_pk_mul_f32 v[248:249], v[248:249], v[250:251] op_sel:[0,1] op_sel_hi:[1,1]
; __device__ __forceinline__ unsigned cvt_pk_bf16(float lo, float hi) { unsigned r; asm volatile("v_cvt_pk_bf16_f32 %0, %1, %2" : "=v"(r) : "v"(lo), "v"(hi)); return r; }
;     __device__ __forceinline__ void operator()(const f32x4 (&acc)[2][2][4][2], const Unit& u, int wr, int wc, int fr, int fq, const float (&rs)[2][4]) const {
;     ...
;         for (int ai = 0; ai < 2; ++ai)
; #pragma unroll
;             for (int m = 0; m < 4; ++m) { bf16_t* rowp = O + (size_t)(row0 + ai * HALF + m * 16) * FF + col0;
;                 float r[8], e[8]; const float rsv = rs[ai][m]; const float c1 = -rsv * LOG2E, c2 = rsv * rsv;
; #pragma unroll
;                 for (int j = 0; j < 8; ++j) { const float gv = acc[ai][0][m][j >> 2][j & 3], uv = acc[ai][1][m][j >> 2][j & 3]; e[j] = gv * c1; r[j] = gv * uv; }
;                 __builtin_amdgcn_sched_barrier(0);
; #pragma unroll
;                 for (int j = 0; j < 8; ++j) e[j] = __builtin_amdgcn_exp2f(e[j]);
;                 __builtin_amdgcn_sched_barrier(0);
; #pragma unroll
;                 for (int j = 0; j < 8; ++j) e[j] = 1.0f + e[j];
;                 __builtin_amdgcn_sched_barrier(0);
; #pragma unroll
;                 for (int j = 0; j < 8; ++j) e[j] = __builtin_amdgcn_rcpf(e[j]);
;                 __builtin_amdgcn_sched_barrier(0);
; #pragma unroll
;                 for (int j = 0; j < 8; ++j) r[j] = r[j] * (c2 * e[j]);
;                 u32x4 w; w.x = cvt_pk_bf16(r[0], r[1]); w.y = cvt_pk_bf16(r[2], r[3]); w.z = cvt_pk_bf16(r[4], r[5]); w.w = cvt_pk_bf16(r[6], r[7]);
;                 *(u32x4*)rowp = w; }
	v_pk_mul_f32 v[94:95], v[94:95], v[242:243]
	v_pk_mul_f32 v[96:97], v[96:97], v[244:245]
	v_pk_mul_f32 v[86:87], v[86:87], v[246:247]
	v_pk_mul_f32 v[88:89], v[88:89], v[248:249]
	v_cvt_pk_bf16_f32 v90, v94, v95
	v_cvt_pk_bf16_f32 v91, v96, v97
	v_cvt_pk_bf16_f32 v92, v86, v87
	v_cvt_pk_bf16_f32 v93, v88, v89
	v_add_u32_e32 v240, 32, v181
	v_mad_i64_i32 v[238:239], s[0:1], v240, s11, v[164:165]
	global_store_dwordx4 v[238:239], v[90:93], off
	v_mul_f32_e32 v250, 0xbfb8aa3b, v160
	v_mul_f32_e32 v251, v160, v160
	v_pk_mul_f32 v[242:243], v[76:77], v[250:251] op_sel_hi:[1,0]
	v_pk_mul_f32 v[244:245], v[78:79], v[250:251] op_sel_hi:[1,0]
	v_pk_mul_f32 v[246:247], v[72:73], v[250:251] op_sel_hi:[1,0]
	v_pk_mul_f32 v[248:249], v[74:75], v[250:251] op_sel_hi:[1,0]
	v_exp_f32_e32 v242, v242
	v_exp_f32_e32 v243, v243
	v_exp_f32_e32 v244, v244
	v_exp_f32_e32 v245, v245
	v_exp_f32_e32 v246, v246
	v_exp_f32_e32 v247, v247
	v_exp_f32_e32 v248, v248
	v_exp_f32_e32 v249, v249
	v_pk_add_f32 v[242:243], v[242:243], 1.0 op_sel_hi:[1,0]
	v_pk_add_f32 v[244:245], v[244:245], 1.0 op_sel_hi:[1,0]
	v_pk_add_f32 v[246:247], v[246:247], 1.0 op_sel_hi:[1,0]
	v_pk_add_f32 v[248:249], v[248:249], 1.0 op_sel_hi:[1,0]
	v_rcp_f32_e32 v242, v242
	v_rcp_f32_e32 v243, v243
	v_rcp_f32_e32 v244, v244
	v_rcp_f32_e32 v245, v245
	v_rcp_f32_e32 v246, v246
	v_rcp_f32_e32 v247, v247
	v_rcp_f32_e32 v248, v248
	v_rcp_f32_e32 v249, v249
	v_pk_mul_f32 v[76:77], v[76:77], v[68:69]
	v_pk_mul_f32 v[78:79], v[78:79], v[70:71]
	v_pk_mul_f32 v[72:73], v[72:73], v[64:65]
	v_pk_mul_f32 v[74:75], v[74:75], v[66:67]
	v_pk_mul_f32 v[242:243], v[242:243], v[250:251] op_sel:[0,1] op_sel_hi:[1,1]
	v_pk_mul_f32 v[244:245], v[244:245], v[250:251] op_sel:[0,1] op_sel_hi:[1,1]
	v_pk_mul_f32 v[246:247], v[246:247], v[250:251] op_sel:[0,1] op_sel_hi:[1,1]
	v_pk_mul_f32 v[248:249], v[248:249], v[250:251] op_sel:[0,1] op_sel_hi:[1,1]
	v_pk_mul_f32 v[76:77], v[76:77], v[242:243]
	v_pk_mul_f32 v[78:79], v[78:79], v[244:245]
	v_pk_mul_f32 v[72:73], v[72:73], v[246:247]
	v_pk_mul_f32 v[74:75], v[74:75], v[248:249]
	v_cvt_pk_bf16_f32 v68, v76, v77
	v_cvt_pk_bf16_f32 v69, v78, v79
	v_cvt_pk_bf16_f32 v70, v72, v73
	v_cvt_pk_bf16_f32 v71, v74, v75
	v_add_u32_e32 v240, 48, v181
	v_mad_i64_i32 v[238:239], s[0:1], v240, s11, v[164:165]
	global_store_dwordx4 v[238:239], v[68:71], off
	v_mul_f32_e32 v250, 0xbfb8aa3b, v159
	v_mul_f32_e32 v251, v159, v159
	v_pk_mul_f32 v[242:243], v[60:61], v[250:251] op_sel_hi:[1,0]
	v_pk_mul_f32 v[244:245], v[62:63], v[250:251] op_sel_hi:[1,0]
	v_pk_mul_f32 v[246:247], v[52:53], v[250:251] op_sel_hi:[1,0]
	v_pk_mul_f32 v[248:249], v[54:55], v[250:251] op_sel_hi:[1,0]
	v_exp_f32_e32 v242, v242
	v_exp_f32_e32 v243, v243
	v_exp_f32_e32 v244, v244
	v_exp_f32_e32 v245, v245
	v_exp_f32_e32 v246, v246
	v_exp_f32_e32 v247, v247
	v_exp_f32_e32 v248, v248
	v_exp_f32_e32 v249, v249
	v_pk_add_f32 v[242:243], v[242:243], 1.0 op_sel_hi:[1,0]
	v_pk_add_f32 v[244:245], v[244:245], 1.0 op_sel_hi:[1,0]
	v_pk_add_f32 v[246:247], v[246:247], 1.0 op_sel_hi:[1,0]
	v_pk_add_f32 v[248:249], v[248:249], 1.0 op_sel_hi:[1,0]
	v_rcp_f32_e32 v242, v242
	v_rcp_f32_e32 v243, v243
	v_rcp_f32_e32 v244, v244
	v_rcp_f32_e32 v245, v245
	v_rcp_f32_e32 v246, v246
	v_rcp_f32_e32 v247, v247
	v_rcp_f32_e32 v248, v248
	v_rcp_f32_e32 v249, v249
	v_pk_mul_f32 v[60:61], v[60:61], v[56:57]
	v_pk_mul_f32 v[62:63], v[62:63], v[58:59]
	v_pk_mul_f32 v[52:53], v[52:53], v[48:49]
	v_pk_mul_f32 v[54:55], v[54:55], v[50:51]
	v_pk_mul_f32 v[242:243], v[242:243], v[250:251] op_sel:[0,1] op_sel_hi:[1,1]
	v_pk_mul_f32 v[244:245], v[244:245], v[250:251] op_sel:[0,1] op_sel_hi:[1,1]
	v_pk_mul_f32 v[246:247], v[246:247], v[250:251] op_sel:[0,1] op_sel_hi:[1,1]
	v_pk_mul_f32 v[248:249], v[248:249], v[250:251] op_sel:[0,1] op_sel_hi:[1,1]
	v_pk_mul_f32 v[60:61], v[60:61], v[242:243]
	v_pk_mul_f32 v[62:63], v[62:63], v[244:245]
	v_pk_mul_f32 v[52:53], v[52:53], v[246:247]
	v_pk_mul_f32 v[54:55], v[54:55], v[248:249]
	v_cvt_pk_bf16_f32 v56, v60, v61
	v_cvt_pk_bf16_f32 v57, v62, v63
	v_cvt_pk_bf16_f32 v58, v52, v53
	v_cvt_pk_bf16_f32 v59, v54, v55
	v_add_u32_e32 v240, 0x80, v181
	v_mad_i64_i32 v[238:239], s[0:1], v240, s11, v[164:165]
	global_store_dwordx4 v[238:239], v[56:59], off
	v_mul_f32_e32 v250, 0xbfb8aa3b, v158
	v_mul_f32_e32 v251, v158, v158
	v_pk_mul_f32 v[242:243], v[44:45], v[250:251] op_sel_hi:[1,0]
	v_pk_mul_f32 v[244:245], v[46:47], v[250:251] op_sel_hi:[1,0]
	v_pk_mul_f32 v[246:247], v[40:41], v[250:251] op_sel_hi:[1,0]
	v_pk_mul_f32 v[248:249], v[42:43], v[250:251] op_sel_hi:[1,0]
	v_exp_f32_e32 v242, v242
	v_exp_f32_e32 v243, v243
	v_exp_f32_e32 v244, v244
	v_exp_f32_e32 v245, v245
	v_exp_f32_e32 v246, v246
	v_exp_f32_e32 v247, v247
	v_exp_f32_e32 v248, v248
	v_exp_f32_e32 v249, v249
	v_pk_add_f32 v[242:243], v[242:243], 1.0 op_sel_hi:[1,0]
	v_pk_add_f32 v[244:245], v[244:245], 1.0 op_sel_hi:[1,0]
	v_pk_add_f32 v[246:247], v[246:247], 1.0 op_sel_hi:[1,0]
	v_pk_add_f32 v[248:249], v[248:249], 1.0 op_sel_hi:[1,0]
	v_rcp_f32_e32 v242, v242
	v_rcp_f32_e32 v243, v243
	v_rcp_f32_e32 v244, v244
	v_rcp_f32_e32 v245, v245
	v_rcp_f32_e32 v246, v246
	v_rcp_f32_e32 v247, v247
	v_rcp_f32_e32 v248, v248
	v_rcp_f32_e32 v249, v249
	v_pk_mul_f32 v[44:45], v[44:45], v[36:37]
	v_pk_mul_f32 v[46:47], v[46:47], v[38:39]
	v_pk_mul_f32 v[40:41], v[40:41], v[32:33]
	v_pk_mul_f32 v[42:43], v[42:43], v[34:35]
	v_pk_mul_f32 v[242:243], v[242:243], v[250:251] op_sel:[0,1] op_sel_hi:[1,1]
	v_pk_mul_f32 v[244:245], v[244:245], v[250:251] op_sel:[0,1] op_sel_hi:[1,1]
	v_pk_mul_f32 v[246:247], v[246:247], v[250:251] op_sel:[0,1] op_sel_hi:[1,1]
; __device__ __forceinline__ unsigned cvt_pk_bf16(float lo, float hi) { unsigned r; asm volatile("v_cvt_pk_bf16_f32 %0, %1, %2" : "=v"(r) : "v"(lo), "v"(hi)); return r; }
;     __device__ __forceinline__ void operator()(const f32x4 (&acc)[2][2][4][2], const Unit& u, int wr, int wc, int fr, int fq, const float (&rs)[2][4]) const {
;     ...
;         for (int ai = 0; ai < 2; ++ai)
; #pragma unroll
;             for (int m = 0; m < 4; ++m) { bf16_t* rowp = O + (size_t)(row0 + ai * HALF + m * 16) * FF + col0;
;                 float r[8], e[8]; const float rsv = rs[ai][m]; const float c1 = -rsv * LOG2E, c2 = rsv * rsv;
; #pragma unroll
;                 for (int j = 0; j < 8; ++j) { const float gv = acc[ai][0][m][j >> 2][j & 3], uv = acc[ai][1][m][j >> 2][j & 3]; e[j] = gv * c1; r[j] = gv * uv; }
;                 __builtin_amdgcn_sched_barrier(0);
; #pragma unroll
;                 for (int j = 0; j < 8; ++j) e[j] = __builtin_amdgcn_exp2f(e[j]);
;                 __builtin_amdgcn_sched_barrier(0);
; #pragma unroll
;                 for (int j = 0; j < 8; ++j) e[j] = 1.0f + e[j];
;                 __builtin_amdgcn_sched_barrier(0);
; #pragma unroll
;                 for (int j = 0; j < 8; ++j) e[j] = __builtin_amdgcn_rcpf(e[j]);
;                 __builtin_amdgcn_sched_barrier(0);
; #pragma unroll
;                 for (int j = 0; j < 8; ++j) r[j] = r[j] * (c2 * e[j]);
;                 u32x4 w; w.x = cvt_pk_bf16(r[0], r[1]); w.y = cvt_pk_bf16(r[2], r[3]); w.z = cvt_pk_bf16(r[4], r[5]); w.w = cvt_pk_bf16(r[6], r[7]);
;                 *(u32x4*)rowp = w; }
	v_pk_mul_f32 v[248:249], v[248:249], v[250:251] op_sel:[0,1] op_sel_hi:[1,1]
	v_pk_mul_f32 v[44:45], v[44:45], v[242:243]
	v_pk_mul_f32 v[46:47], v[46:47], v[244:245]
	v_pk_mul_f32 v[40:41], v[40:41], v[246:247]
	v_pk_mul_f32 v[42:43], v[42:43], v[248:249]
	v_cvt_pk_bf16_f32 v36, v44, v45
	v_cvt_pk_bf16_f32 v37, v46, v47
	v_cvt_pk_bf16_f32 v38, v40, v41
	v_cvt_pk_bf16_f32 v39, v42, v43
	v_add_u32_e32 v240, 0x90, v181
	v_mad_i64_i32 v[238:239], s[0:1], v240, s11, v[164:165]
	global_store_dwordx4 v[238:239], v[36:39], off
	v_mul_f32_e32 v250, 0xbfb8aa3b, v157
	v_mul_f32_e32 v251, v157, v157
	v_pk_mul_f32 v[242:243], v[28:29], v[250:251] op_sel_hi:[1,0]
	v_pk_mul_f32 v[244:245], v[30:31], v[250:251] op_sel_hi:[1,0]
	v_pk_mul_f32 v[246:247], v[20:21], v[250:251] op_sel_hi:[1,0]
	v_pk_mul_f32 v[248:249], v[22:23], v[250:251] op_sel_hi:[1,0]
	v_exp_f32_e32 v242, v242
	v_exp_f32_e32 v243, v243
	v_exp_f32_e32 v244, v244
	v_exp_f32_e32 v245, v245
	v_exp_f32_e32 v246, v246
	v_exp_f32_e32 v247, v247
	v_exp_f32_e32 v248, v248
	v_exp_f32_e32 v249, v249
	v_pk_add_f32 v[242:243], v[242:243], 1.0 op_sel_hi:[1,0]
	v_pk_add_f32 v[244:245], v[244:245], 1.0 op_sel_hi:[1,0]
	v_pk_add_f32 v[246:247], v[246:247], 1.0 op_sel_hi:[1,0]
	v_pk_add_f32 v[248:249], v[248:249], 1.0 op_sel_hi:[1,0]
	v_rcp_f32_e32 v242, v242
	v_rcp_f32_e32 v243, v243
	v_rcp_f32_e32 v244, v244
	v_rcp_f32_e32 v245, v245
	v_rcp_f32_e32 v246, v246
	v_rcp_f32_e32 v247, v247
	v_rcp_f32_e32 v248, v248
	v_rcp_f32_e32 v249, v249
	v_pk_mul_f32 v[28:29], v[28:29], v[24:25]
	v_pk_mul_f32 v[30:31], v[30:31], v[26:27]
	v_pk_mul_f32 v[20:21], v[20:21], v[16:17]
	v_pk_mul_f32 v[22:23], v[22:23], v[18:19]
	v_pk_mul_f32 v[242:243], v[242:243], v[250:251] op_sel:[0,1] op_sel_hi:[1,1]
	v_pk_mul_f32 v[244:245], v[244:245], v[250:251] op_sel:[0,1] op_sel_hi:[1,1]
	v_pk_mul_f32 v[246:247], v[246:247], v[250:251] op_sel:[0,1] op_sel_hi:[1,1]
	v_pk_mul_f32 v[248:249], v[248:249], v[250:251] op_sel:[0,1] op_sel_hi:[1,1]
	v_pk_mul_f32 v[28:29], v[28:29], v[242:243]
	v_pk_mul_f32 v[30:31], v[30:31], v[244:245]
	v_pk_mul_f32 v[20:21], v[20:21], v[246:247]
	v_pk_mul_f32 v[22:23], v[22:23], v[248:249]
	v_cvt_pk_bf16_f32 v24, v28, v29
	v_cvt_pk_bf16_f32 v25, v30, v31
	v_cvt_pk_bf16_f32 v26, v20, v21
	v_cvt_pk_bf16_f32 v27, v22, v23
	v_add_u32_e32 v240, 0xa0, v181
	v_mad_i64_i32 v[238:239], s[0:1], v240, s11, v[164:165]
	global_store_dwordx4 v[238:239], v[24:27], off
	v_mul_f32_e32 v250, 0xbfb8aa3b, v156
	v_mul_f32_e32 v251, v156, v156
	v_pk_mul_f32 v[242:243], v[12:13], v[250:251] op_sel_hi:[1,0]
	v_pk_mul_f32 v[244:245], v[14:15], v[250:251] op_sel_hi:[1,0]
	v_pk_mul_f32 v[246:247], v[8:9], v[250:251] op_sel_hi:[1,0]
	v_pk_mul_f32 v[248:249], v[10:11], v[250:251] op_sel_hi:[1,0]
	v_exp_f32_e32 v242, v242
	v_exp_f32_e32 v243, v243
	v_exp_f32_e32 v244, v244
	v_exp_f32_e32 v245, v245
	v_exp_f32_e32 v246, v246
	v_exp_f32_e32 v247, v247
	v_exp_f32_e32 v248, v248
	v_exp_f32_e32 v249, v249
	v_pk_add_f32 v[242:243], v[242:243], 1.0 op_sel_hi:[1,0]
	v_pk_add_f32 v[244:245], v[244:245], 1.0 op_sel_hi:[1,0]
	v_pk_add_f32 v[246:247], v[246:247], 1.0 op_sel_hi:[1,0]
	v_pk_add_f32 v[248:249], v[248:249], 1.0 op_sel_hi:[1,0]
	v_rcp_f32_e32 v242, v242
	v_rcp_f32_e32 v243, v243
	v_rcp_f32_e32 v244, v244
	v_rcp_f32_e32 v245, v245
	v_rcp_f32_e32 v246, v246
	v_rcp_f32_e32 v247, v247
	v_rcp_f32_e32 v248, v248
	v_rcp_f32_e32 v249, v249
	v_pk_mul_f32 v[12:13], v[12:13], v[4:5]
	v_pk_mul_f32 v[14:15], v[14:15], v[6:7]
	v_pk_mul_f32 v[8:9], v[8:9], v[0:1]
	v_pk_mul_f32 v[10:11], v[10:11], v[2:3]
	v_pk_mul_f32 v[242:243], v[242:243], v[250:251] op_sel:[0,1] op_sel_hi:[1,1]
	v_pk_mul_f32 v[244:245], v[244:245], v[250:251] op_sel:[0,1] op_sel_hi:[1,1]
	v_pk_mul_f32 v[246:247], v[246:247], v[250:251] op_sel:[0,1] op_sel_hi:[1,1]
	v_pk_mul_f32 v[248:249], v[248:249], v[250:251] op_sel:[0,1] op_sel_hi:[1,1]
	v_pk_mul_f32 v[12:13], v[12:13], v[242:243]
	v_pk_mul_f32 v[14:15], v[14:15], v[244:245]
	v_pk_mul_f32 v[8:9], v[8:9], v[246:247]
	v_pk_mul_f32 v[10:11], v[10:11], v[248:249]
	v_cvt_pk_bf16_f32 v4, v12, v13
	v_cvt_pk_bf16_f32 v5, v14, v15
	v_cvt_pk_bf16_f32 v6, v8, v9
	v_cvt_pk_bf16_f32 v7, v10, v11
	v_add_u32_e32 v240, 0xb0, v181
	v_mad_i64_i32 v[238:239], s[0:1], v240, s11, v[164:165]
	s_and_b64 vcc, exec, s[40:41]
	s_mov_b64 s[40:41], -1
	global_store_dwordx4 v[238:239], v[4:7], off
	s_cbranch_vccnz .LBB0_600
; #define PG8_BAR __builtin_amdgcn_s_barrier()
; template <class Epi, bool ALIGN_EPI>
; __device__ __forceinline__ void gemm_phase(LAS unsigned char* lds, const Gemm g, const StaticOrder S, const Epi E) {
;     ...
;         cur = nxt; cA = nA; cB = nB; ++ui;
;         if constexpr (ALIGN_EPI) { if (wr == 1) PG8_BAR; }
	s_waitcnt vmcnt(8)
	v_add_f32_e32 v232, v200, v201
	v_add_f32_e32 v233, v202, v203
	v_add_f32_e32 v145, v232, v233
	v_add_f32_e32 v232, v204, v205
	v_add_f32_e32 v233, v206, v207
	v_add_f32_e32 v144, v232, v233
	v_add_f32_e32 v232, v208, v209
	v_add_f32_e32 v233, v210, v211
	v_add_f32_e32 v147, v232, v233
	v_add_f32_e32 v232, v212, v213
	v_add_f32_e32 v233, v214, v215
	v_add_f32_e32 v146, v232, v233
	v_add_f32_e32 v232, v216, v217
	v_add_f32_e32 v233, v218, v219
	v_add_f32_e32 v149, v232, v233
	v_add_f32_e32 v232, v220, v221
	v_add_f32_e32 v233, v222, v223
	v_add_f32_e32 v148, v232, v233
	v_add_f32_e32 v232, v224, v225
	v_add_f32_e32 v233, v226, v227
	v_add_f32_e32 v155, v232, v233
	v_add_f32_e32 v232, v228, v229
	v_add_f32_e32 v233, v230, v231
	v_add_f32_e32 v154, v232, v233
	ds_swizzle_b32 v0, v145 offset:swizzle(SWAP,16)
	ds_swizzle_b32 v2, v144 offset:swizzle(SWAP,16)
	ds_swizzle_b32 v4, v146 offset:swizzle(SWAP,16)
	ds_swizzle_b32 v8, v148 offset:swizzle(SWAP,16)
	ds_swizzle_b32 v10, v154 offset:swizzle(SWAP,16)
	ds_swizzle_b32 v238, v147 offset:swizzle(SWAP,16)
	ds_swizzle_b32 v239, v149 offset:swizzle(SWAP,16)
	ds_swizzle_b32 v240, v155 offset:swizzle(SWAP,16)
	s_waitcnt lgkmcnt(0)
	v_add_f32_e32 v1, v145, v0
	v_add_f32_e32 v0, v144, v2
	v_mov_b32_e32 v3, v1
	v_mov_b32_e32 v2, v0
	s_nop 0
	v_permlane32_swap_b32_e32 v1, v3
	v_permlane32_swap_b32_e32 v0, v2
	v_pk_add_f32 v[0:1], v[0:1], v[2:3]
	s_mov_b32 s0, 0x358637bd
	v_mov_b64_e32 v[6:7], s[0:1]
	v_pk_fma_f32 v[0:1], v[0:1], s[90:91], v[6:7] op_sel_hi:[1,0,0]
	s_andn2_b64 vcc, exec, s[62:63]
	s_waitcnt lgkmcnt(0)
	v_add_f32_e32 v3, v147, v238
	v_add_f32_e32 v2, v146, v4
	v_mov_b32_e32 v5, v3
	v_mov_b32_e32 v4, v2
	s_nop 0
	v_permlane32_swap_b32_e32 v3, v5
	v_permlane32_swap_b32_e32 v2, v4
	v_pk_add_f32 v[2:3], v[2:3], v[4:5]
	v_pk_fma_f32 v[2:3], v[2:3], s[90:91], v[6:7] op_sel_hi:[1,0,0]
	v_cmp_gt_f32_e64 s[40:41], s10, v0
	v_cmp_gt_f32_e64 s[42:43], s10, v1
	v_cmp_gt_f32_e64 s[44:45], s10, v2
	s_waitcnt lgkmcnt(0)
	v_add_f32_e32 v5, v149, v239
	v_add_f32_e32 v4, v148, v8
	v_mov_b32_e32 v9, v5
	v_mov_b32_e32 v8, v4
	s_nop 0
	v_permlane32_swap_b32_e32 v5, v9
	v_permlane32_swap_b32_e32 v4, v8
	v_pk_add_f32 v[4:5], v[4:5], v[8:9]
	v_pk_fma_f32 v[4:5], v[4:5], s[90:91], v[6:7] op_sel_hi:[1,0,0]
	v_cmp_gt_f32_e64 s[48:49], s10, v3
	v_cmp_gt_f32_e64 s[46:47], s10, v4
	v_cmp_gt_f32_e64 s[50:51], s10, v5
	s_waitcnt lgkmcnt(0)
	v_add_f32_e32 v9, v155, v240
	v_add_f32_e32 v8, v154, v10
	v_mov_b32_e32 v11, v9
	v_mov_b32_e32 v10, v8
	s_nop 0
	v_permlane32_swap_b32_e32 v9, v11
	v_permlane32_swap_b32_e32 v8, v10
	v_pk_add_f32 v[8:9], v[8:9], v[10:11]
	s_nop 0
	v_pk_fma_f32 v[6:7], v[8:9], s[90:91], v[6:7] op_sel_hi:[1,0,0]
	s_nop 0
	v_cmp_gt_f32_e64 s[52:53], s10, v6
	v_cmp_gt_f32_e64 s[54:55], s10, v7
	s_cbranch_vccnz .LBB0_599
	s_barrier
	s_branch .LBB0_599
